# diff attention loop: counted vmcnt waits keep the next K/V tile set in flight across a tile (Q-fragment wait hoisted before the loop), on top of LDS-staged finalize
# baseline (speedup 1.0000x reference)
; #define ATT_LOAD(S, j) do { rk##S = *(const u32x4*)(ksrc + (size_t)(j) * 64 * 1024); if (!DIFF && tid < 256) rk2##S = *(const u32x4*)(k2src + (size_t)(j) * 64 * 32); \
;         rv0##S = *(const u32x4*)(vsrc + (size_t)(j) * 64 * 1024); if (DIFF) rv1##S = *(const u32x4*)(vsrc + (size_t)(j) * 64 * 1024 + 32 * 1024); } while (0)
; #define ATT_STORE(S, bufp) do { *(LAS u32x4*)((bufp) + kdst) = rk##S; if (!DIFF && tid < 256) *(LAS u32x4*)((bufp) + k2dst) = rk2##S; \
;         *(LAS u32x4*)((bufp) + vdst) = rv0##S; if (DIFF) *(LAS u32x4*)((bufp) + vdst + 32 * PV) = rv1##S; } while (0)
; template <bool DIFF>
; __device__ __forceinline__ void attn_unit_coop(const Grp& G, int b, int h, int qb, int n, LAS unsigned char* lds, const int tid_in) {
;     ...
;         AttnState<DQK, DV> st; attn_init(st);
;         if (DIFF) { const bf16* qp = G.QD + (seq0 + qrow0 + q) * 1024 + h * 128 + n * 64 + hi * 8;
; #pragma unroll
;             for (int ks = 0; ks < 4; ++ks) st.qf[ks] = *(const bf16x8*)(qp + ks * 16);
;         } else { const bf16* qn = G.QN + (seq0 + qrow0 + q) * 1024 + h * 64 + hi * 8; const bf16* qr = G.QR + (seq0 + qrow0 + q) * 512 + h * 32 + hi * 8;
; #pragma unroll
;             for (int ks = 0; ks < 4; ++ks) st.qf[ks] = *(const bf16x8*)(qn + ks * 16);
; #pragma unroll
;             for (int ks = 0; ks < 2; ++ks) st.qf[4 + ks] = *(const bf16x8*)(qr + ks * 16);
;         }
;         const bf16* ksrc = (DIFF ? G.KD + h * 128 + n * 64 : G.KN + h * 64) + (seq0 + (tid >> 3)) * 1024 + (tid & 7) * 8;
;         const int kdst = (tid >> 3) * PK + (tid & 7) * 16;
;         const bf16* k2src = G.KR + (seq0 + ((tid & 255) >> 2)) * 32 + (tid & 3) * 8;
;         const int k2dst = ((tid & 255) >> 2) * PK + 128 + (tid & 3) * 16;
;         const bf16* vsrc = DIFF ? G.VD + (seq0 + (tid >> 4)) * 1024 + h * 128 + (tid & 15) * 8 : G.VM + (seq0 + (tid >> 3)) * 1024 + h * 64 + (tid & 7) * 8;
;         const int vdst = DIFF ? KB + (tid >> 4) * PV + (tid & 15) * 16 : KB + (tid >> 3) * PV + (tid & 7) * 16;
;         u32x4 rkA, rk2A = {0u, 0u, 0u, 0u}, rv0A, rv1A = {0u, 0u, 0u, 0u}, rkB = {0u, 0u, 0u, 0u}, rk2B = {0u, 0u, 0u, 0u}, rv0B = {0u, 0u, 0u, 0u}, rv1B = {0u, 0u, 0u, 0u};
;     ...
;         ATT_LOAD(A, 0); ATT_STORE(A, tiles);
;         __syncthreads();
;         ATT_LOAD(A, 1);
.LBB0_519:
	v_mov_b32_e32 v28, v212
	v_mov_b32_e32 v15, v185
	v_ashrrev_i32_e32 v12, 3, v28
	v_ashrrev_i32_e32 v13, 31, v12
	v_lshl_add_u64 v[0:1], s[24:25], 0, v[12:13]
	v_lshlrev_b64 v[0:1], 11, v[0:1]
	v_lshlrev_b32_e32 v2, 4, v28
	v_ashrrev_i32_e32 v18, 4, v28
	v_lshl_add_u64 v[0:1], s[30:31], 0, v[0:1]
	v_and_b32_e32 v14, 0x70, v2
	v_ashrrev_i32_e32 v19, 31, v18
	v_lshl_add_u64 v[16:17], v[0:1], 0, v[14:15]
	v_lshl_add_u64 v[0:1], s[24:25], 0, v[18:19]
	v_lshlrev_b64 v[0:1], 11, v[0:1]
	v_lshl_add_u64 v[0:1], s[14:15], 0, v[0:1]
	v_and_b32_e32 v20, 0xf0, v2
	v_mov_b32_e32 v21, v185
	v_lshl_add_u64 v[22:23], v[0:1], 0, v[20:21]
	global_load_dwordx4 v[0:3], v[16:17], off
	global_load_dwordx4 v[4:7], v[22:23], off
	v_add_co_u32_e32 v8, vcc, s53, v22
	s_xor_b64 s[36:37], s[0:1], -1
	s_nop 0
	v_addc_co_u32_e32 v9, vcc, 0, v23, vcc
	global_load_dwordx4 v[8:11], v[8:9], off
	s_and_b64 s[0:1], s[0:1], exec
	s_cselect_b32 s0, s48, s90
	v_readfirstlane_b32 s1, v28
	s_lshl_b32 s2, s0, 8
	s_ashr_i32 s3, s1, 1
	s_lshl_b32 s7, s0, 2
	s_ashr_i32 s40, s1, 7
	s_and_b32 s41, s1, 0x3fffffc0
	v_mad_u64_u32 v[24:25], s[0:1], v12, s76, v[14:15]
	s_andn2_b32 s3, s3, 31
	s_movk_i32 s0, 0x140
	v_mad_u64_u32 v[26:27], s[0:1], v18, s0, v[20:21]
	s_add_i32 s42, s3, s2
	s_ashr_i32 s0, s42, 31
	s_add_u32 s38, s24, s42
	v_and_b32_e32 v194, 31, v28
	s_addc_u32 s39, s25, s0
	v_add_u32_e32 v214, 0, v24
	v_or_b32_e32 v24, s38, v194
	v_add_co_u32_e32 v16, vcc, s62, v16
	v_mov_b32_e32 v25, s39
	v_bfe_u32 v191, v28, 5, 1
	v_addc_co_u32_e32 v17, vcc, 0, v17, vcc
	v_lshlrev_b64 v[24:25], 11, v[24:25]
	v_lshlrev_b32_e32 v184, 4, v191
	v_add_u32_e32 v215, 0, v26
	v_add_co_u32_e32 v26, vcc, s62, v22
	v_lshl_add_u64 v[24:25], s[28:29], 0, v[24:25]
	s_nop 0
	v_addc_co_u32_e32 v27, vcc, 0, v23, vcc
	s_mov_b32 s0, 0x30000
	v_lshl_add_u64 v[24:25], v[24:25], 0, v[184:185]
	v_add_co_u32_e32 v22, vcc, s0, v22
	global_load_dwordx4 v[112:115], v[24:25], off
	global_load_dwordx4 v[116:119], v[24:25], off offset:32
	global_load_dwordx4 v[120:123], v[24:25], off offset:64
	global_load_dwordx4 v[124:127], v[24:25], off offset:96
	v_addc_co_u32_e32 v23, vcc, 0, v23, vcc
	s_lshl_b32 s0, s41, 2
	s_add_i32 s6, s7, 4
	s_add_i32 s7, s40, s7
	s_add_i32 s40, s0, 0
	v_mov_b32_e32 v142, v185
	v_mov_b32_e32 v143, v185
	v_mov_b32_e32 v48, v185
	v_mov_b32_e32 v49, v185
	v_mov_b32_e32 v62, v185
	v_mov_b32_e32 v63, v185
	v_mov_b32_e32 v140, v185
	v_mov_b32_e32 v141, v185
	v_mov_b32_e32 v50, v185
	v_mov_b32_e32 v51, v185
	v_mov_b32_e32 v52, v185
	v_mov_b32_e32 v53, v185
	v_mov_b32_e32 v54, v185
	v_mov_b32_e32 v55, v185
	v_mov_b32_e32 v56, v185
	v_mov_b32_e32 v57, v185
	v_mov_b32_e32 v58, v185
	v_mov_b32_e32 v59, v185
	s_waitcnt vmcnt(6)
	ds_write_b128 v214, v[0:3] offset:8192
	s_waitcnt vmcnt(5)
	ds_write_b128 v215, v[4:7] offset:17408
	s_waitcnt vmcnt(4)
	ds_write_b128 v215, v[8:11] offset:27648
	s_waitcnt lgkmcnt(0)
	s_barrier
	global_load_dwordx4 v[128:131], v[16:17], off
	global_load_dwordx4 v[132:135], v[26:27], off
	global_load_dwordx4 v[136:139], v[22:23], off
	v_and_b32_e32 v0, 63, v28
	v_lshlrev_b32_e32 v1, 2, v191
	v_lshrrev_b32_e32 v3, 2, v28
	v_and_b32_e32 v4, 16, v28
	v_lshlrev_b32_e32 v5, 2, v28
	v_and_or_b32 v4, v5, 12, v4
	v_cmp_gt_u32_e64 s[0:1], 32, v0
	v_and_or_b32 v0, v3, 3, v1
	v_lshlrev_b32_e32 v4, 1, v4
	v_mul_u32_u24_e32 v0, 0x140, v0
	v_add3_u32 v217, 0, v4, v0
	v_or_b32_e32 v0, s42, v194
	v_sub_u32_e32 v218, v1, v0
	v_sub_u32_e32 v0, v1, v194
	v_subrev_u32_e32 v0, s3, v0
	v_subrev_u32_e32 v219, s2, v0
	s_mul_i32 s98, s85, 5
	s_add_i32 s98, s98, 0x11380
	v_lshl_add_u32 v225, v218, 2, s98
	v_lshlrev_b64 v[0:1], 11, v[18:19]
	v_or_b32_e32 v0, v0, v20
	v_lshl_add_u64 v[196:197], s[22:23], 0, v[0:1]
	v_lshlrev_b64 v[0:1], 11, v[12:13]
	v_mad_u32_u24 v2, v194, s76, 0
	v_or_b32_e32 v0, v0, v14
	v_lshl_add_u64 v[198:199], s[34:35], 0, v[0:1]
	v_mov_b32_e32 v60, v185
	v_mov_b32_e32 v61, v185
	v_add_u32_e32 v221, v2, v184
	v_mov_b64_e32 v[32:33], v[48:49]
	v_mov_b64_e32 v[16:17], v[48:49]
	v_mov_b64_e32 v[0:1], v[48:49]
	v_mov_b64_e32 v[78:79], v[62:63]
	v_mov_b64_e32 v[146:147], v[142:143]
	v_mov_b64_e32 v[150:151], v[142:143]
	s_mov_b32 s58, 0
	v_lshl_add_u32 v216, v194, 2, s40
	v_add_u32_e32 v213, s40, v184
	s_sub_i32 s92, 0, s42
	v_mov_b32_e32 v220, 0
	v_mov_b64_e32 v[34:35], v[50:51]
	v_mov_b64_e32 v[36:37], v[52:53]
	v_mov_b64_e32 v[38:39], v[54:55]
	v_mov_b64_e32 v[40:41], v[56:57]
	v_mov_b64_e32 v[42:43], v[58:59]
	v_mov_b64_e32 v[44:45], v[60:61]
	v_mov_b64_e32 v[46:47], v[62:63]
	v_mov_b64_e32 v[18:19], v[50:51]
	v_mov_b64_e32 v[20:21], v[52:53]
	v_mov_b64_e32 v[22:23], v[54:55]
	v_mov_b64_e32 v[24:25], v[56:57]
	v_mov_b64_e32 v[26:27], v[58:59]
	v_mov_b64_e32 v[28:29], v[60:61]
	v_mov_b64_e32 v[30:31], v[62:63]
	v_mov_b64_e32 v[2:3], v[50:51]
	v_mov_b64_e32 v[4:5], v[52:53]
	v_mov_b64_e32 v[6:7], v[54:55]
	v_mov_b64_e32 v[8:9], v[56:57]
	v_mov_b64_e32 v[10:11], v[58:59]
	v_mov_b64_e32 v[12:13], v[60:61]
	v_mov_b64_e32 v[14:15], v[62:63]
	v_mov_b64_e32 v[76:77], v[60:61]
	v_mov_b64_e32 v[74:75], v[58:59]
	v_mov_b64_e32 v[72:73], v[56:57]
	v_mov_b64_e32 v[70:71], v[54:55]
	v_mov_b64_e32 v[68:69], v[52:53]
	v_mov_b64_e32 v[66:67], v[50:51]
	v_mov_b64_e32 v[64:65], v[48:49]
	v_mov_b32_e32 v184, 0
	v_mov_b64_e32 v[144:145], v[140:141]
	v_mov_b64_e32 v[148:149], v[140:141]
	s_mov_b32 s59, 0
	s_waitcnt vmcnt(3)

; #define LAS __attribute__((address_space(3)))
; template <int DQK, int DV, bool HAS_BIAS>
; __device__ __forceinline__ void attn_tile(AttnState<DQK, DV>& st, const LAS unsigned char* Kt, const LAS unsigned char* Vt, int bias_mode, const LAS float* tab, int rel0, int nkeys, bool first, LAS float* wsf, int lane) {
;     ...
;     const LAS unsigned char* kp = Kt + q * PK + hi * 16;
;     bf16x8 ka[KS], kb[KS];
; #pragma unroll
;     for (int ks = 0; ks < KS; ++ks) { ka[ks] = *(const LAS bf16x8*)(kp + ks * 32); kb[ks] = *(const LAS bf16x8*)(kp + 32 * PK + ks * 32); }
;     if (HAS_BIAS && bias_mode == 2) {
;         asm volatile("" ::: "memory");
; #pragma unroll
;         for (int r = 0; r < 16; ++r) {
;             const int k = crow(r, hi);
;             const int i0 = min(max(rel0 + k + 128, 0), 191), i1 = min(max(rel0 + k + 160, 0), 191);
;             p0[r] = tab[i0] + st.negm[r]; p1[r] = tab[i1] + st.negm[r];
;         }
;         p0 = __builtin_amdgcn_mfma_f32_32x32x16_bf16(ka[0], st.qf[0], p0, 0, 0, 0);
;         p1 = __builtin_amdgcn_mfma_f32_32x32x16_bf16(kb[0], st.qf[0], p1, 0, 0, 0);
;     } else {
;         p0 = __builtin_amdgcn_mfma_f32_32x32x16_bf16(ka[0], st.qf[0], st.negm, 0, 0, 0);
;         p1 = __builtin_amdgcn_mfma_f32_32x32x16_bf16(kb[0], st.qf[0], st.negm, 0, 0, 0);
;     }
; #pragma unroll
;     for (int ks = 1; ks < KS; ++ks) {
;         p0 = __builtin_amdgcn_mfma_f32_32x32x16_bf16(ka[ks], st.qf[ks], p0, 0, 0, 0);
;         p1 = __builtin_amdgcn_mfma_f32_32x32x16_bf16(kb[ks], st.qf[ks], p1, 0, 0, 0);
;     }
;     const int q4 = (lane & 15) >> 2, blk = (lane >> 4) & 1, pp = lane & 3;
;     const LAS unsigned char* vp = Vt + (4 * hi + q4) * PV + (16 * blk + 4 * pp) * 2;
;     s16x4 vlo[2][4], vhi[2][4];
; #pragma unroll
;     for (int s4 = 0; s4 < 4; ++s4) { vlo[0][s4] = vtr(vp + (16 * s4) * PV); vhi[0][s4] = vtr(vp + (16 * s4 + 8) * PV); }
;     __builtin_amdgcn_sched_barrier(0);
;     if (nkeys < 64) {
; #pragma unroll
;         for (int r = 0; r < 16; ++r) { const int k = crow(r, hi); if (k >= nkeys) p0[r] = -1e30f; if (k + 32 >= nkeys) p1[r] = -1e30f; }
;     }
;     float mxa = __builtin_fmaxf(__builtin_fmaxf(p0[0], p0[1]), p1[0]), mxb = __builtin_fmaxf(__builtin_fmaxf(p0[2], p0[3]), p1[1]);
;     mxa = __builtin_fmaxf(__builtin_fmaxf(mxa, p1[2]), p1[3]);
; #pragma unroll
;     for (int r = 4; r < 16; r += 4) {
.LBB0_522:
	s_cmp_gt_i32 s59, s7
	s_cbranch_scc1 .LBB0_536
	ds_read_b128 v[180:183], v221 offset:8192
	ds_read_b128 v[160:163], v221 offset:8224
	ds_read_b128 v[176:179], v221 offset:12800
	ds_read_b128 v[164:167], v221 offset:12832
	ds_read_b128 v[156:159], v221 offset:8256
	ds_read_b128 v[152:155], v221 offset:8288
	ds_read_b128 v[172:175], v221 offset:12864
	ds_read_b128 v[168:171], v221 offset:12896
	s_add_i32 s2, s92, s58
	s_add_i32 s2, s2, 63
	s_cmpk_lt_i32 s2, 0xff81
	s_mov_b64 s[2:3], -1
	s_cbranch_scc0 .LBB0_525
	s_waitcnt lgkmcnt(7)
	v_mfma_f32_32x32x16_bf16 v[80:95], v[180:183], v[112:115], v[64:79]
	s_mov_b64 s[2:3], 0
	s_waitcnt lgkmcnt(5)
	v_mfma_f32_32x32x16_bf16 v[96:111], v[176:179], v[112:115], v[64:79]
.LBB0_525:
	s_andn2_b64 vcc, exec, s[2:3]
	s_cbranch_vccnz .LBB0_527
	s_nop 6
	v_lshl_add_u32 v224, s58, 2, v225
	ds_read_b32 v80, v224 offset:0
	ds_read_b32 v96, v224 offset:128
	ds_read_b32 v81, v224 offset:4
	ds_read_b32 v97, v224 offset:132
	ds_read_b32 v82, v224 offset:8
	ds_read_b32 v98, v224 offset:136
	ds_read_b32 v83, v224 offset:12
	ds_read_b32 v99, v224 offset:140
	ds_read_b32 v84, v224 offset:32
	ds_read_b32 v100, v224 offset:160
	ds_read_b32 v85, v224 offset:36
	ds_read_b32 v101, v224 offset:164
	ds_read_b32 v86, v224 offset:40
	ds_read_b32 v102, v224 offset:168
	ds_read_b32 v87, v224 offset:44
	ds_read_b32 v103, v224 offset:172
	ds_read_b32 v88, v224 offset:64
	ds_read_b32 v104, v224 offset:192
	ds_read_b32 v89, v224 offset:68
	ds_read_b32 v105, v224 offset:196
	ds_read_b32 v90, v224 offset:72
	ds_read_b32 v106, v224 offset:200
	ds_read_b32 v91, v224 offset:76
	ds_read_b32 v107, v224 offset:204
	ds_read_b32 v92, v224 offset:96
	ds_read_b32 v108, v224 offset:224
	ds_read_b32 v93, v224 offset:100
	ds_read_b32 v109, v224 offset:228
	ds_read_b32 v94, v224 offset:104
	ds_read_b32 v110, v224 offset:232
	ds_read_b32 v95, v224 offset:108
	ds_read_b32 v111, v224 offset:236
	s_waitcnt lgkmcnt(0)
	v_pk_add_f32 v[94:95], v[78:79], v[94:95]
	s_waitcnt lgkmcnt(3)
	v_pk_add_f32 v[92:93], v[76:77], v[92:93]
	v_pk_add_f32 v[90:91], v[74:75], v[90:91]
	v_pk_add_f32 v[88:89], v[72:73], v[88:89]
	v_pk_add_f32 v[86:87], v[70:71], v[86:87]
	v_pk_add_f32 v[84:85], v[68:69], v[84:85]
	v_pk_add_f32 v[82:83], v[66:67], v[82:83]
	v_pk_add_f32 v[80:81], v[64:65], v[80:81]
	s_waitcnt lgkmcnt(1)
	v_pk_add_f32 v[110:111], v[78:79], v[110:111]
	s_waitcnt lgkmcnt(0)
	v_pk_add_f32 v[108:109], v[76:77], v[108:109]
	v_pk_add_f32 v[106:107], v[74:75], v[106:107]
	v_pk_add_f32 v[104:105], v[72:73], v[104:105]
	v_pk_add_f32 v[102:103], v[70:71], v[102:103]
	v_pk_add_f32 v[100:101], v[68:69], v[100:101]
	v_pk_add_f32 v[98:99], v[66:67], v[98:99]
	v_pk_add_f32 v[96:97], v[64:65], v[96:97]
	v_mfma_f32_32x32x16_bf16 v[80:95], v[180:183], v[112:115], v[80:95]
	v_mfma_f32_32x32x16_bf16 v[96:111], v[176:179], v[112:115], v[96:111]
.LBB0_527:
	s_waitcnt lgkmcnt(6)
	v_mfma_f32_32x32x16_bf16 v[80:95], v[160:163], v[116:119], v[80:95]
	s_cmp_eq_u32 s58, 0
	s_cselect_b64 s[2:3], -1, 0
	s_cmp_lg_u32 s58, 0
	s_waitcnt lgkmcnt(4)
	v_mfma_f32_32x32x16_bf16 v[96:111], v[164:167], v[116:119], v[96:111]
	s_waitcnt lgkmcnt(3)
	v_mfma_f32_32x32x16_bf16 v[80:95], v[156:159], v[120:123], v[80:95]
	s_waitcnt lgkmcnt(1)
	v_mfma_f32_32x32x16_bf16 v[96:111], v[172:175], v[120:123], v[96:111]
	v_mfma_f32_32x32x16_bf16 v[80:95], v[152:155], v[124:127], v[80:95]
	ds_read_b64_tr_b16 v[152:153], v217 offset:17408
	ds_read_b64_tr_b16 v[154:155], v217 offset:19968
	ds_read_b64_tr_b16 v[156:157], v217 offset:17472
	ds_read_b64_tr_b16 v[158:159], v217 offset:20032
	ds_read_b64_tr_b16 v[160:161], v217 offset:17536
	ds_read_b64_tr_b16 v[162:163], v217 offset:20096
	ds_read_b64_tr_b16 v[164:165], v217 offset:17600
	ds_read_b64_tr_b16 v[166:167], v217 offset:20160
	s_waitcnt lgkmcnt(8)
	v_mfma_f32_32x32x16_bf16 v[96:111], v[168:171], v[124:127], v[96:111]
	ds_read_b64_tr_b16 v[226:227], v217 offset:22528
	ds_read_b64_tr_b16 v[228:229], v217 offset:25088
	ds_read_b64_tr_b16 v[230:231], v217 offset:22592
	ds_read_b64_tr_b16 v[232:233], v217 offset:25152
	ds_read_b64_tr_b16 v[234:235], v217 offset:22656
	ds_read_b64_tr_b16 v[236:237], v217 offset:25216
	ds_read_b64_tr_b16 v[238:239], v217 offset:22720
	ds_read_b64_tr_b16 v[240:241], v217 offset:25280
	s_nop 1
	v_max_f32_e32 v168, v81, v81
	v_max_f32_e32 v169, v80, v80
	v_max_f32_e32 v168, v169, v168
	s_nop 6
	v_max3_f32 v169, v82, v83, v97
	v_max3_f32 v168, v168, v96, v98
	v_max3_f32 v168, v168, v99, v84
	v_max3_f32 v169, v169, v86, v87
	v_max3_f32 v168, v168, v85, v100
	v_max3_f32 v169, v169, v102, v103
	v_max3_f32 v168, v168, v101, v88
	v_max3_f32 v169, v169, v90, v91
	v_max3_f32 v168, v168, v89, v104
	v_max3_f32 v169, v169, v106, v107
	v_max3_f32 v168, v168, v105, v92
	v_max3_f32 v169, v169, v94, v95
	v_max3_f32 v168, v168, v93, v108
	v_max3_f32 v169, v169, v110, v111
	v_max3_f32 v168, v168, v109, v169
	v_mov_b32_e32 v169, v168
	s_nop 1
	v_permlane32_swap_b32_e32 v168, v169
	v_max_f32_e32 v169, v169, v169
	v_max_f32_e32 v168, v168, v168
	v_max_f32_e32 v168, v168, v169
	s_cbranch_scc0 .LBB0_529
	v_cmp_lt_f32_e32 vcc, s77, v168
	s_cmp_lg_u64 vcc, 0
	s_cselect_b64 s[44:45], -1, 0
	s_cbranch_execz .LBB0_530
	s_branch .LBB0_531

; #define ATT_LOAD(S, j) do { rk##S = *(const u32x4*)(ksrc + (size_t)(j) * 64 * 1024); if (!DIFF && tid < 256) rk2##S = *(const u32x4*)(k2src + (size_t)(j) * 64 * 32); \
;         rv0##S = *(const u32x4*)(vsrc + (size_t)(j) * 64 * 1024); if (DIFF) rv1##S = *(const u32x4*)(vsrc + (size_t)(j) * 64 * 1024 + 32 * 1024); } while (0)
; #define ATT_STORE(S, bufp) do { *(LAS u32x4*)((bufp) + kdst) = rk##S; if (!DIFF && tid < 256) *(LAS u32x4*)((bufp) + k2dst) = rk2##S; \
;         *(LAS u32x4*)((bufp) + vdst) = rv0##S; if (DIFF) *(LAS u32x4*)((bufp) + vdst + 32 * PV) = rv1##S; } while (0)
; #define ATT_COMPUTE(j, bufp) do { if ((j) < my_nt) { const int kb_ = 64 * (j); const int mode_ = DIFF ? ((kb_ + 63 - qrow0 <= -128) ? 1 : 2) : 0; \
;         attn_tile<DQK, DV, DIFF>(st, (bufp), (bufp) + KB, mode_, tab, kb_ - (qrow0 + q), 64, (j) == 0, wsf, lane); } } while (0)
; template <bool DIFF>
; __device__ __forceinline__ void attn_unit_coop(const Grp& G, int b, int h, int qb, int n, LAS unsigned char* lds, const int tid_in) {
;     ...
;             if (j + 2 < NT) ATT_LOAD(B, j + 2);
;             ATT_COMPUTE(j, b0);
;             ATT_STORE(A, b1);
;             __syncthreads();
;             if (j + 3 < NT) ATT_LOAD(A, j + 3);
.LBB0_536:
	s_and_b64 vcc, exec, s[42:43]
	s_cbranch_vccz .Lsta_last
	s_waitcnt vmcnt(5)
	ds_write_b128 v214, v[128:131] offset:37888
	s_waitcnt vmcnt(4)
	ds_write_b128 v215, v[132:135] offset:47104
	s_waitcnt vmcnt(3)
	ds_write_b128 v215, v[136:139] offset:57344
	s_branch .Lsta_done
.Lsta_last:
	s_waitcnt vmcnt(2)
	ds_write_b128 v214, v[128:131] offset:37888
	s_waitcnt vmcnt(1)
	ds_write_b128 v215, v[132:135] offset:47104
	s_waitcnt vmcnt(0)
	ds_write_b128 v215, v[136:139] offset:57344
.Lsta_done:
	s_add_i32 s2, s59, 3
	s_cmp_ge_u32 s2, s6
	s_waitcnt lgkmcnt(0)
	s_barrier
	s_cbranch_scc0 .LBB0_542
	s_cmp_ge_i32 s59, s7
	s_cbranch_scc0 .LBB0_543

; #define ATT_LOAD(S, j) do { rk##S = *(const u32x4*)(ksrc + (size_t)(j) * 64 * 1024); if (!DIFF && tid < 256) rk2##S = *(const u32x4*)(k2src + (size_t)(j) * 64 * 32); \
;         rv0##S = *(const u32x4*)(vsrc + (size_t)(j) * 64 * 1024); if (DIFF) rv1##S = *(const u32x4*)(vsrc + (size_t)(j) * 64 * 1024 + 32 * 1024); } while (0)
; #define ATT_STORE(S, bufp) do { *(LAS u32x4*)((bufp) + kdst) = rk##S; if (!DIFF && tid < 256) *(LAS u32x4*)((bufp) + k2dst) = rk2##S; \
;         *(LAS u32x4*)((bufp) + vdst) = rv0##S; if (DIFF) *(LAS u32x4*)((bufp) + vdst + 32 * PV) = rv1##S; } while (0)
; #define ATT_COMPUTE(j, bufp) do { if ((j) < my_nt) { const int kb_ = 64 * (j); const int mode_ = DIFF ? ((kb_ + 63 - qrow0 <= -128) ? 1 : 2) : 0; \
;         attn_tile<DQK, DV, DIFF>(st, (bufp), (bufp) + KB, mode_, tab, kb_ - (qrow0 + q), 64, (j) == 0, wsf, lane); } } while (0)
; template <bool DIFF>
; __device__ __forceinline__ void attn_unit_coop(const Grp& G, int b, int h, int qb, int n, LAS unsigned char* lds, const int tid_in) {
;     ...
;             if (j + 3 < NT) ATT_LOAD(A, j + 3);
;             ATT_COMPUTE(j + 1, b1);
;             if (j + 2 < NT) ATT_STORE(B, b0);
;             __syncthreads();
.LBB0_539:
	s_waitcnt vmcnt(5)
	ds_write_b128 v214, v[140:143] offset:8192
	s_waitcnt vmcnt(4)
	ds_write_b128 v215, v[144:147] offset:17408
	s_waitcnt vmcnt(3)
	ds_write_b128 v215, v[148:151] offset:27648
